# grid barrier: leaders invalidate (and wait) before the cross-XCD arrival, waiting workgroups invalidate L1 at arrival and leave on the cross-XCD release word directly; the per-XCD release hop is gone
# baseline (speedup 1.0000x reference)
; __device__ __forceinline__ unsigned xb_ld(unsigned* p)              { return __hip_atomic_load(p, __ATOMIC_RELAXED, __HIP_MEMORY_SCOPE_AGENT); }
; __device__ __forceinline__ unsigned xb_add(unsigned* p, unsigned v) { return __hip_atomic_fetch_add(p, v, __ATOMIC_RELAXED, __HIP_MEMORY_SCOPE_AGENT); }
; #define XB_SPIN(cond, bar) do { unsigned _sp = 0; while (cond) { __builtin_amdgcn_s_sleep(1); \
;     if ((++_sp & 255u) == 0u) { if (xb_ld(&(bar)[XB_TMO])) break; if (_sp > XB_SPIN_CAP) { atomicAdd(&(bar)[XB_TMO], 1u); break; } } } } while (0)
; __device__ __forceinline__ void xcd_barrier(const XcdBarrier& b) {
;     ...
;         const unsigned old = xb_add(&bar[XB_XSUB(b.x)], 1u);
;         const unsigned gen = old / nloc;
;         if (old + 1u == (gen + 1u) * nloc) {
;             __builtin_amdgcn_fence(__ATOMIC_RELEASE, "agent");
;             asm volatile("s_waitcnt vmcnt(0)" ::: "memory");
;             const unsigned og = xb_add(&bar[XB_TOP], 1u);
;             const unsigned tg = og / nx;
;             if (og + 1u == (tg + 1u) * nx) xb_add(&bar[XB_TOPGEN], 1u);
;             else XB_SPIN(xb_ld(&bar[XB_TOPGEN]) == tg, bar);
;             __builtin_amdgcn_fence(__ATOMIC_ACQUIRE, "agent");
;             xb_add(&bar[XB_XGEN(b.x)], 1u);
;             asm volatile("s_waitcnt vmcnt(0)" ::: "memory");
;         } else {
;             XB_SPIN(xb_ld(&bar[XB_XGEN(b.x)]) == gen, bar);
;             __builtin_amdgcn_fence(__ATOMIC_ACQUIRE, "agent");
;             asm volatile("s_waitcnt vmcnt(0)" ::: "memory");
.LBB0_125:
	s_or_b64 exec, exec, s[8:9]
	v_cvt_f32_u32_e32 v4, v2
	s_waitcnt vmcnt(0)
	v_readfirstlane_b32 s3, v3
	v_sub_u32_e32 v3, 0, v2
	v_rcp_iflag_f32_e32 v4, v4
	v_add_u32_e32 v5, s3, v1
	v_mul_f32_e32 v4, 0x4f7ffffe, v4
	v_cvt_u32_f32_e32 v4, v4
	v_mul_lo_u32 v1, v3, v4
	v_mul_hi_u32 v1, v4, v1
	v_add_u32_e32 v1, v4, v1
	v_mul_hi_u32 v1, v5, v1
	v_mul_lo_u32 v3, v1, v2
	v_sub_u32_e32 v3, v5, v3
	v_add_u32_e32 v4, 1, v1
	v_cmp_ge_u32_e32 vcc, v3, v2
	s_nop 1
	v_cndmask_b32_e32 v1, v1, v4, vcc
	v_sub_u32_e32 v4, v3, v2
	v_cndmask_b32_e32 v3, v3, v4, vcc
	v_add_u32_e32 v4, 1, v1
	v_cmp_ge_u32_e32 vcc, v3, v2
	v_add_u32_e32 v3, 1, v5
	s_nop 0
	v_cndmask_b32_e32 v1, v1, v4, vcc
	v_mul_lo_u32 v4, v2, v1
	v_add_u32_e32 v2, v4, v2
	v_cmp_ne_u32_e32 vcc, v3, v2
	s_and_saveexec_b64 s[6:7], vcc
	s_xor_b64 s[6:7], exec, s[6:7]
	s_cbranch_execz .LBB0_139
	s_waitcnt lgkmcnt(0)
	buffer_inv sc1
	v_mov_b32_e32 v0, 0x2f83000
	global_load_dword v0, v0, s[58:59] offset:1280 sc1
	s_add_u32 s12, s58, 0x2f83500
	s_addc_u32 s13, s59, 0
	s_waitcnt vmcnt(0)
	v_cmp_eq_u32_e32 vcc, v0, v1
	s_and_saveexec_b64 s[8:9], vcc
	s_cbranch_execz .LBB0_138
	s_add_u32 s10, s58, 0x2f80200
	s_addc_u32 s11, s59, 0
	s_mov_b32 s3, 1
	s_mov_b64 s[14:15], 0
	v_mov_b32_e32 v0, 0
	s_branch .LBB0_129

; __device__ __forceinline__ unsigned xb_add(unsigned* p, unsigned v) { return __hip_atomic_fetch_add(p, v, __ATOMIC_RELAXED, __HIP_MEMORY_SCOPE_AGENT); }
; __device__ __forceinline__ void xcd_barrier(const XcdBarrier& b) {
;     ...
;         if (old + 1u == (gen + 1u) * nloc) {
;             __builtin_amdgcn_fence(__ATOMIC_RELEASE, "agent");
;             asm volatile("s_waitcnt vmcnt(0)" ::: "memory");
;             const unsigned og = xb_add(&bar[XB_TOP], 1u);
.LBB0_139:
	s_andn2_saveexec_b64 s[6:7], s[6:7]
	s_cbranch_execz .LBB0_159
	s_mov_b64 s[6:7], exec
	buffer_wbl2 sc1
	s_waitcnt lgkmcnt(0)
	s_waitcnt vmcnt(0)
	buffer_inv sc1
	s_waitcnt vmcnt(0)
	v_mbcnt_lo_u32_b32 v1, s6, 0
	v_mbcnt_hi_u32_b32 v1, s7, v1
	v_cmp_eq_u32_e32 vcc, 0, v1
	s_and_saveexec_b64 s[8:9], vcc
	s_cbranch_execz .LBB0_142
	s_bcnt1_i32_b64 s3, s[6:7]
	v_mov_b32_e32 v2, 0x2f83000
	v_mov_b32_e32 v3, s3
	global_atomic_add v2, v2, v3, s[58:59] offset:1024 sc0

; __device__ __forceinline__ unsigned xb_add(unsigned* p, unsigned v) { return __hip_atomic_fetch_add(p, v, __ATOMIC_RELAXED, __HIP_MEMORY_SCOPE_AGENT); }
; __device__ __forceinline__ void xcd_barrier(const XcdBarrier& b) {
;     ...
;             __builtin_amdgcn_fence(__ATOMIC_ACQUIRE, "agent");
;             xb_add(&bar[XB_XGEN(b.x)], 1u);
;             asm volatile("s_waitcnt vmcnt(0)" ::: "memory");
.LBB0_156:
	s_or_b64 exec, exec, s[6:7]
	s_mov_b64 s[6:7], exec
	v_mbcnt_lo_u32_b32 v0, s6, 0
	v_mbcnt_hi_u32_b32 v0, s7, v0
	v_cmp_eq_u32_e32 vcc, 0, v0
	s_waitcnt vmcnt(0)
	s_and_saveexec_b64 s[8:9], vcc
	s_cbranch_execz .LBB0_158
	s_bcnt1_i32_b64 s3, s[6:7]
	v_mov_b32_e32 v0, 0x2000
	v_mov_b32_e32 v1, s3
.LBB0_158:
	s_or_b64 exec, exec, s[8:9]
	s_waitcnt vmcnt(0)

; __device__ __forceinline__ unsigned xb_add(unsigned* p, unsigned v) { return __hip_atomic_fetch_add(p, v, __ATOMIC_RELAXED, __HIP_MEMORY_SCOPE_AGENT); }
; __device__ __forceinline__ void xcd_barrier(const XcdBarrier& b) {
;     ...
;             __builtin_amdgcn_fence(__ATOMIC_ACQUIRE, "agent");
;             xb_add(&bar[XB_XGEN(b.x)], 1u);
;             asm volatile("s_waitcnt vmcnt(0)" ::: "memory");
.LBB0_220:
	s_or_b64 exec, exec, s[6:7]
	s_mov_b64 s[6:7], exec
	v_mbcnt_lo_u32_b32 v0, s6, 0
	v_mbcnt_hi_u32_b32 v0, s7, v0
	v_cmp_eq_u32_e32 vcc, 0, v0
	s_waitcnt vmcnt(0)
	s_and_saveexec_b64 s[8:9], vcc
	s_cbranch_execz .LBB0_222
	s_bcnt1_i32_b64 s3, s[6:7]
	v_mov_b32_e32 v0, 0x2000
	v_mov_b32_e32 v1, s3
.LBB0_222:
	s_or_b64 exec, exec, s[8:9]
	s_waitcnt vmcnt(0)

; __device__ __forceinline__ unsigned xb_add(unsigned* p, unsigned v) { return __hip_atomic_fetch_add(p, v, __ATOMIC_RELAXED, __HIP_MEMORY_SCOPE_AGENT); }
; __device__ __forceinline__ void xcd_barrier(const XcdBarrier& b) {
;     ...
;             __builtin_amdgcn_fence(__ATOMIC_ACQUIRE, "agent");
;             xb_add(&bar[XB_XGEN(b.x)], 1u);
;             asm volatile("s_waitcnt vmcnt(0)" ::: "memory");
.LBB0_428:
	s_or_b64 exec, exec, s[6:7]
	s_mov_b64 s[6:7], exec
	v_mbcnt_lo_u32_b32 v0, s6, 0
	v_mbcnt_hi_u32_b32 v0, s7, v0
	v_cmp_eq_u32_e32 vcc, 0, v0
	s_waitcnt vmcnt(0)
	s_and_saveexec_b64 s[8:9], vcc
	s_cbranch_execz .LBB0_430
	s_bcnt1_i32_b64 s3, s[6:7]
	v_mov_b32_e32 v0, 0x2000
	v_mov_b32_e32 v1, s3
.LBB0_430:
	s_or_b64 exec, exec, s[8:9]
	s_waitcnt vmcnt(0)

; __device__ __forceinline__ unsigned xb_add(unsigned* p, unsigned v) { return __hip_atomic_fetch_add(p, v, __ATOMIC_RELAXED, __HIP_MEMORY_SCOPE_AGENT); }
; __device__ __forceinline__ void xcd_barrier(const XcdBarrier& b) {
;     ...
;             __builtin_amdgcn_fence(__ATOMIC_ACQUIRE, "agent");
;             xb_add(&bar[XB_XGEN(b.x)], 1u);
;             asm volatile("s_waitcnt vmcnt(0)" ::: "memory");
.LBB0_524:
	s_or_b64 exec, exec, s[6:7]
	s_mov_b64 s[6:7], exec
	v_mbcnt_lo_u32_b32 v0, s6, 0
	v_mbcnt_hi_u32_b32 v0, s7, v0
	v_cmp_eq_u32_e32 vcc, 0, v0
	s_waitcnt vmcnt(0)
	s_and_saveexec_b64 s[8:9], vcc
	s_cbranch_execz .LBB0_526
	s_bcnt1_i32_b64 s3, s[6:7]
	v_mov_b32_e32 v0, 0x2000
	v_mov_b32_e32 v1, s3
.LBB0_526:
	s_or_b64 exec, exec, s[8:9]
	s_waitcnt vmcnt(0)

; __device__ __forceinline__ unsigned xb_add(unsigned* p, unsigned v) { return __hip_atomic_fetch_add(p, v, __ATOMIC_RELAXED, __HIP_MEMORY_SCOPE_AGENT); }
; __device__ __forceinline__ void xcd_barrier(const XcdBarrier& b) {
;     ...
;             __builtin_amdgcn_fence(__ATOMIC_ACQUIRE, "agent");
;             xb_add(&bar[XB_XGEN(b.x)], 1u);
;             asm volatile("s_waitcnt vmcnt(0)" ::: "memory");
.LBB0_696:
	s_or_b64 exec, exec, s[6:7]
	s_mov_b64 s[6:7], exec
	v_mbcnt_lo_u32_b32 v0, s6, 0
	v_mbcnt_hi_u32_b32 v0, s7, v0
	v_cmp_eq_u32_e32 vcc, 0, v0
	s_waitcnt vmcnt(0)
	s_and_saveexec_b64 s[8:9], vcc
	s_cbranch_execz .LBB0_698
	s_bcnt1_i32_b64 s3, s[6:7]
	v_mov_b32_e32 v0, 0x2000
	v_mov_b32_e32 v1, s3
.LBB0_698:
	s_or_b64 exec, exec, s[8:9]
	s_waitcnt vmcnt(0)

; __device__ __forceinline__ unsigned xb_add(unsigned* p, unsigned v) { return __hip_atomic_fetch_add(p, v, __ATOMIC_RELAXED, __HIP_MEMORY_SCOPE_AGENT); }
; __device__ __forceinline__ void xcd_barrier(const XcdBarrier& b) {
;     ...
;             __builtin_amdgcn_fence(__ATOMIC_ACQUIRE, "agent");
;             xb_add(&bar[XB_XGEN(b.x)], 1u);
;             asm volatile("s_waitcnt vmcnt(0)" ::: "memory");
.LBB0_751:
	s_or_b64 exec, exec, s[6:7]
	s_mov_b64 s[6:7], exec
	v_mbcnt_lo_u32_b32 v0, s6, 0
	v_mbcnt_hi_u32_b32 v0, s7, v0
	v_cmp_eq_u32_e32 vcc, 0, v0
	s_waitcnt vmcnt(0)
	s_and_saveexec_b64 s[8:9], vcc
	s_cbranch_execz .LBB0_753
	s_bcnt1_i32_b64 s3, s[6:7]
	v_mov_b32_e32 v0, 0x2000
	v_mov_b32_e32 v1, s3
.LBB0_753:
	s_or_b64 exec, exec, s[8:9]
	s_waitcnt vmcnt(0)

; __device__ __forceinline__ unsigned xb_add(unsigned* p, unsigned v) { return __hip_atomic_fetch_add(p, v, __ATOMIC_RELAXED, __HIP_MEMORY_SCOPE_AGENT); }
; __device__ __forceinline__ void xcd_barrier(const XcdBarrier& b) {
;     ...
;             __builtin_amdgcn_fence(__ATOMIC_ACQUIRE, "agent");
;             xb_add(&bar[XB_XGEN(b.x)], 1u);
;             asm volatile("s_waitcnt vmcnt(0)" ::: "memory");
.LBB0_841:
	s_or_b64 exec, exec, s[6:7]
	s_mov_b64 s[6:7], exec
	v_mbcnt_lo_u32_b32 v0, s6, 0
	v_mbcnt_hi_u32_b32 v0, s7, v0
	v_cmp_eq_u32_e32 vcc, 0, v0
	s_waitcnt vmcnt(0)
	s_and_saveexec_b64 s[8:9], vcc
	s_cbranch_execz .LBB0_843
	s_bcnt1_i32_b64 s3, s[6:7]
	v_mov_b32_e32 v0, 0x2000
	v_mov_b32_e32 v1, s3
.LBB0_843:
	s_or_b64 exec, exec, s[8:9]
	s_waitcnt vmcnt(0)

; __device__ __forceinline__ unsigned xb_add(unsigned* p, unsigned v) { return __hip_atomic_fetch_add(p, v, __ATOMIC_RELAXED, __HIP_MEMORY_SCOPE_AGENT); }
; __device__ __forceinline__ void xcd_barrier(const XcdBarrier& b) {
;     ...
;             __builtin_amdgcn_fence(__ATOMIC_ACQUIRE, "agent");
;             xb_add(&bar[XB_XGEN(b.x)], 1u);
;             asm volatile("s_waitcnt vmcnt(0)" ::: "memory");
.LBB0_896:
	s_or_b64 exec, exec, s[6:7]
	s_mov_b64 s[6:7], exec
	v_mbcnt_lo_u32_b32 v0, s6, 0
	v_mbcnt_hi_u32_b32 v0, s7, v0
	v_cmp_eq_u32_e32 vcc, 0, v0
	s_waitcnt vmcnt(0)
	s_and_saveexec_b64 s[8:9], vcc
	s_cbranch_execz .LBB0_898
	s_bcnt1_i32_b64 s3, s[6:7]
	v_mov_b32_e32 v0, 0x2000
	v_mov_b32_e32 v1, s3
.LBB0_898:
	s_or_b64 exec, exec, s[8:9]
	s_waitcnt vmcnt(0)

; __device__ __forceinline__ unsigned xb_add(unsigned* p, unsigned v) { return __hip_atomic_fetch_add(p, v, __ATOMIC_RELAXED, __HIP_MEMORY_SCOPE_AGENT); }
; __device__ __forceinline__ void xcd_barrier(const XcdBarrier& b) {
;     ...
;             __builtin_amdgcn_fence(__ATOMIC_ACQUIRE, "agent");
;             xb_add(&bar[XB_XGEN(b.x)], 1u);
;             asm volatile("s_waitcnt vmcnt(0)" ::: "memory");
.LBB0_960:
	s_or_b64 exec, exec, s[6:7]
	s_mov_b64 s[6:7], exec
	v_mbcnt_lo_u32_b32 v0, s6, 0
	v_mbcnt_hi_u32_b32 v0, s7, v0
	v_cmp_eq_u32_e32 vcc, 0, v0
	s_waitcnt vmcnt(0)
	s_and_saveexec_b64 s[8:9], vcc
	s_cbranch_execz .LBB0_962
	s_bcnt1_i32_b64 s3, s[6:7]
	v_mov_b32_e32 v0, 0x2000
	v_mov_b32_e32 v1, s3
.LBB0_962:
	s_or_b64 exec, exec, s[8:9]
	s_waitcnt vmcnt(0)

; __device__ __forceinline__ unsigned xb_ld(unsigned* p)              { return __hip_atomic_load(p, __ATOMIC_RELAXED, __HIP_MEMORY_SCOPE_AGENT); }
; __device__ __forceinline__ unsigned xb_add(unsigned* p, unsigned v) { return __hip_atomic_fetch_add(p, v, __ATOMIC_RELAXED, __HIP_MEMORY_SCOPE_AGENT); }
; #define XB_SPIN(cond, bar) do { unsigned _sp = 0; while (cond) { __builtin_amdgcn_s_sleep(1); \
;     if ((++_sp & 255u) == 0u) { if (xb_ld(&(bar)[XB_TMO])) break; if (_sp > XB_SPIN_CAP) { atomicAdd(&(bar)[XB_TMO], 1u); break; } } } } while (0)
; __device__ __forceinline__ void xcd_barrier(const XcdBarrier& b) {
;     ...
;         const unsigned old = xb_add(&bar[XB_XSUB(b.x)], 1u);
;         const unsigned gen = old / nloc;
;         if (old + 1u == (gen + 1u) * nloc) {
;             __builtin_amdgcn_fence(__ATOMIC_RELEASE, "agent");
;             asm volatile("s_waitcnt vmcnt(0)" ::: "memory");
;             const unsigned og = xb_add(&bar[XB_TOP], 1u);
;             const unsigned tg = og / nx;
;             if (og + 1u == (tg + 1u) * nx) xb_add(&bar[XB_TOPGEN], 1u);
;             else XB_SPIN(xb_ld(&bar[XB_TOPGEN]) == tg, bar);
;             __builtin_amdgcn_fence(__ATOMIC_ACQUIRE, "agent");
;             xb_add(&bar[XB_XGEN(b.x)], 1u);
;             asm volatile("s_waitcnt vmcnt(0)" ::: "memory");
;         } else {
;             XB_SPIN(xb_ld(&bar[XB_XGEN(b.x)]) == gen, bar);
;             __builtin_amdgcn_fence(__ATOMIC_ACQUIRE, "agent");
;             asm volatile("s_waitcnt vmcnt(0)" ::: "memory");
.LBB0_1043:
	s_or_b64 exec, exec, s[10:11]
	v_cvt_f32_u32_e32 v4, v2
	s_waitcnt vmcnt(0)
	v_readfirstlane_b32 s3, v3
	v_sub_u32_e32 v3, 0, v2
	v_rcp_iflag_f32_e32 v4, v4
	v_add_u32_e32 v5, s3, v1
	v_mul_f32_e32 v4, 0x4f7ffffe, v4
	v_cvt_u32_f32_e32 v4, v4
	v_mul_lo_u32 v1, v3, v4
	v_mul_hi_u32 v1, v4, v1
	v_add_u32_e32 v1, v4, v1
	v_mul_hi_u32 v1, v5, v1
	v_mul_lo_u32 v3, v1, v2
	v_sub_u32_e32 v3, v5, v3
	v_add_u32_e32 v4, 1, v1
	v_cmp_ge_u32_e32 vcc, v3, v2
	s_nop 1
	v_cndmask_b32_e32 v1, v1, v4, vcc
	v_sub_u32_e32 v4, v3, v2
	v_cndmask_b32_e32 v3, v3, v4, vcc
	v_add_u32_e32 v4, 1, v1
	v_cmp_ge_u32_e32 vcc, v3, v2
	v_add_u32_e32 v3, 1, v5
	s_nop 0
	v_cndmask_b32_e32 v1, v1, v4, vcc
	v_mul_lo_u32 v4, v2, v1
	v_add_u32_e32 v2, v4, v2
	v_cmp_ne_u32_e32 vcc, v3, v2
	s_and_saveexec_b64 s[6:7], vcc
	s_xor_b64 s[6:7], exec, s[6:7]
	s_cbranch_execz .LBB0_1057
	s_waitcnt lgkmcnt(0)
	buffer_inv sc1
	v_mov_b32_e32 v0, 0x2f83000
	global_load_dword v0, v0, s[58:59] offset:1280 sc1
	s_add_u32 s14, s58, 0x2f83500
	s_addc_u32 s15, s59, 0
	s_waitcnt vmcnt(0)
	v_cmp_eq_u32_e32 vcc, v0, v1
	s_and_saveexec_b64 s[10:11], vcc
	s_cbranch_execz .LBB0_1056
	s_add_u32 s12, s58, 0x2f80200
	s_addc_u32 s13, s59, 0
	s_mov_b32 s3, 1
	s_mov_b64 s[16:17], 0
	v_mov_b32_e32 v0, 0
	s_branch .LBB0_1047

; __device__ __forceinline__ unsigned xb_add(unsigned* p, unsigned v) { return __hip_atomic_fetch_add(p, v, __ATOMIC_RELAXED, __HIP_MEMORY_SCOPE_AGENT); }
; __device__ __forceinline__ void xcd_barrier(const XcdBarrier& b) {
;     ...
;         if (old + 1u == (gen + 1u) * nloc) {
;             __builtin_amdgcn_fence(__ATOMIC_RELEASE, "agent");
;             asm volatile("s_waitcnt vmcnt(0)" ::: "memory");
;             const unsigned og = xb_add(&bar[XB_TOP], 1u);
.LBB0_1057:
	s_andn2_saveexec_b64 s[6:7], s[6:7]
	s_cbranch_execz .LBB0_1077
	s_mov_b64 s[6:7], exec
	buffer_wbl2 sc1
	s_waitcnt lgkmcnt(0)
	s_waitcnt vmcnt(0)
	buffer_inv sc1
	s_waitcnt vmcnt(0)
	v_mbcnt_lo_u32_b32 v1, s6, 0
	v_mbcnt_hi_u32_b32 v1, s7, v1
	v_cmp_eq_u32_e32 vcc, 0, v1
	s_and_saveexec_b64 s[10:11], vcc
	s_cbranch_execz .LBB0_1060
	s_bcnt1_i32_b64 s3, s[6:7]
	v_mov_b32_e32 v2, 0x2f83000
	v_mov_b32_e32 v3, s3
	global_atomic_add v2, v2, v3, s[58:59] offset:1024 sc0

; __device__ __forceinline__ unsigned xb_add(unsigned* p, unsigned v) { return __hip_atomic_fetch_add(p, v, __ATOMIC_RELAXED, __HIP_MEMORY_SCOPE_AGENT); }
; __device__ __forceinline__ void xcd_barrier(const XcdBarrier& b) {
;     ...
;             __builtin_amdgcn_fence(__ATOMIC_ACQUIRE, "agent");
;             xb_add(&bar[XB_XGEN(b.x)], 1u);
;             asm volatile("s_waitcnt vmcnt(0)" ::: "memory");
.LBB0_1074:
	s_or_b64 exec, exec, s[6:7]
	s_mov_b64 s[6:7], exec
	v_mbcnt_lo_u32_b32 v0, s6, 0
	v_mbcnt_hi_u32_b32 v0, s7, v0
	v_cmp_eq_u32_e32 vcc, 0, v0
	s_waitcnt vmcnt(0)
	s_and_saveexec_b64 s[10:11], vcc
	s_cbranch_execz .LBB0_1076
	s_bcnt1_i32_b64 s3, s[6:7]
	v_mov_b32_e32 v0, 0x2000
	v_mov_b32_e32 v1, s3
.LBB0_1076:
	s_or_b64 exec, exec, s[10:11]
	s_waitcnt vmcnt(0)

; __device__ __forceinline__ unsigned xb_add(unsigned* p, unsigned v) { return __hip_atomic_fetch_add(p, v, __ATOMIC_RELAXED, __HIP_MEMORY_SCOPE_AGENT); }
; __device__ __forceinline__ void xcd_barrier(const XcdBarrier& b) {
;     ...
;             __builtin_amdgcn_fence(__ATOMIC_ACQUIRE, "agent");
;             xb_add(&bar[XB_XGEN(b.x)], 1u);
;             asm volatile("s_waitcnt vmcnt(0)" ::: "memory");
.LBB0_1129:
	s_or_b64 exec, exec, s[6:7]
	s_mov_b64 s[6:7], exec
	v_mbcnt_lo_u32_b32 v0, s6, 0
	v_mbcnt_hi_u32_b32 v0, s7, v0
	v_cmp_eq_u32_e32 vcc, 0, v0
	s_waitcnt vmcnt(0)
	s_and_saveexec_b64 s[10:11], vcc
	s_cbranch_execz .LBB0_1131
	s_bcnt1_i32_b64 s3, s[6:7]
	v_mov_b32_e32 v0, 0x2000
	v_mov_b32_e32 v1, s3
.LBB0_1131:
	s_or_b64 exec, exec, s[10:11]
	s_waitcnt vmcnt(0)

; __device__ __forceinline__ unsigned xb_ld(unsigned* p)              { return __hip_atomic_load(p, __ATOMIC_RELAXED, __HIP_MEMORY_SCOPE_AGENT); }
; __device__ __forceinline__ unsigned xb_add(unsigned* p, unsigned v) { return __hip_atomic_fetch_add(p, v, __ATOMIC_RELAXED, __HIP_MEMORY_SCOPE_AGENT); }
; #define XB_SPIN(cond, bar) do { unsigned _sp = 0; while (cond) { __builtin_amdgcn_s_sleep(1); \
;     if ((++_sp & 255u) == 0u) { if (xb_ld(&(bar)[XB_TMO])) break; if (_sp > XB_SPIN_CAP) { atomicAdd(&(bar)[XB_TMO], 1u); break; } } } } while (0)
; __device__ __forceinline__ void xcd_barrier(const XcdBarrier& b) {
;     ...
;         const unsigned old = xb_add(&bar[XB_XSUB(b.x)], 1u);
;         const unsigned gen = old / nloc;
;         if (old + 1u == (gen + 1u) * nloc) {
;             __builtin_amdgcn_fence(__ATOMIC_RELEASE, "agent");
;             asm volatile("s_waitcnt vmcnt(0)" ::: "memory");
;             const unsigned og = xb_add(&bar[XB_TOP], 1u);
;             const unsigned tg = og / nx;
;             if (og + 1u == (tg + 1u) * nx) xb_add(&bar[XB_TOPGEN], 1u);
;             else XB_SPIN(xb_ld(&bar[XB_TOPGEN]) == tg, bar);
;             __builtin_amdgcn_fence(__ATOMIC_ACQUIRE, "agent");
;             xb_add(&bar[XB_XGEN(b.x)], 1u);
;             asm volatile("s_waitcnt vmcnt(0)" ::: "memory");
;         } else {
;             XB_SPIN(xb_ld(&bar[XB_XGEN(b.x)]) == gen, bar);
;             __builtin_amdgcn_fence(__ATOMIC_ACQUIRE, "agent");
;             asm volatile("s_waitcnt vmcnt(0)" ::: "memory");
.LBB0_1188:
	s_or_b64 exec, exec, s[6:7]
	v_cvt_f32_u32_e32 v4, v2
	s_waitcnt vmcnt(0)
	v_readfirstlane_b32 s4, v3
	v_sub_u32_e32 v3, 0, v2
	v_rcp_iflag_f32_e32 v4, v4
	v_add_u32_e32 v5, s4, v1
	v_mul_f32_e32 v4, 0x4f7ffffe, v4
	v_cvt_u32_f32_e32 v4, v4
	v_mul_lo_u32 v1, v3, v4
	v_mul_hi_u32 v1, v4, v1
	v_add_u32_e32 v1, v4, v1
	v_mul_hi_u32 v1, v5, v1
	v_mul_lo_u32 v3, v1, v2
	v_sub_u32_e32 v3, v5, v3
	v_add_u32_e32 v4, 1, v1
	v_cmp_ge_u32_e32 vcc, v3, v2
	s_nop 1
	v_cndmask_b32_e32 v1, v1, v4, vcc
	v_sub_u32_e32 v4, v3, v2
	v_cndmask_b32_e32 v3, v3, v4, vcc
	v_add_u32_e32 v4, 1, v1
	v_cmp_ge_u32_e32 vcc, v3, v2
	v_add_u32_e32 v3, 1, v5
	s_nop 0
	v_cndmask_b32_e32 v1, v1, v4, vcc
	v_mul_lo_u32 v4, v2, v1
	v_add_u32_e32 v2, v4, v2
	v_cmp_ne_u32_e32 vcc, v3, v2
	s_and_saveexec_b64 s[4:5], vcc
	s_xor_b64 s[4:5], exec, s[4:5]
	s_cbranch_execz .LBB0_1202
	s_waitcnt lgkmcnt(0)
	buffer_inv sc1
	v_mov_b32_e32 v0, 0x2f83000
	global_load_dword v0, v0, s[58:59] offset:1280 sc1
	s_add_u32 s10, s58, 0x2f83500
	s_addc_u32 s11, s59, 0
	s_waitcnt vmcnt(0)
	v_cmp_eq_u32_e32 vcc, v0, v1
	s_and_saveexec_b64 s[6:7], vcc
	s_cbranch_execz .LBB0_1201
	s_add_u32 s8, s58, 0x2f80200
	s_addc_u32 s9, s59, 0
	s_mov_b32 s22, 1
	s_mov_b64 s[12:13], 0
	v_mov_b32_e32 v0, 0
	s_branch .LBB0_1192

; __device__ __forceinline__ unsigned xb_add(unsigned* p, unsigned v) { return __hip_atomic_fetch_add(p, v, __ATOMIC_RELAXED, __HIP_MEMORY_SCOPE_AGENT); }
; __device__ __forceinline__ void xcd_barrier(const XcdBarrier& b) {
;     ...
;         if (old + 1u == (gen + 1u) * nloc) {
;             __builtin_amdgcn_fence(__ATOMIC_RELEASE, "agent");
;             asm volatile("s_waitcnt vmcnt(0)" ::: "memory");
;             const unsigned og = xb_add(&bar[XB_TOP], 1u);
.LBB0_1202:
	s_andn2_saveexec_b64 s[4:5], s[4:5]
	s_cbranch_execz .LBB0_1222
	s_mov_b64 s[4:5], exec
	buffer_wbl2 sc1
	s_waitcnt lgkmcnt(0)
	s_waitcnt vmcnt(0)
	buffer_inv sc1
	s_waitcnt vmcnt(0)
	v_mbcnt_lo_u32_b32 v1, s4, 0
	v_mbcnt_hi_u32_b32 v1, s5, v1
	v_cmp_eq_u32_e32 vcc, 0, v1
	s_and_saveexec_b64 s[6:7], vcc
	s_cbranch_execz .LBB0_1205
	s_bcnt1_i32_b64 s4, s[4:5]
	v_mov_b32_e32 v2, 0x2f83000
	v_mov_b32_e32 v3, s4
	global_atomic_add v2, v2, v3, s[58:59] offset:1024 sc0

; __device__ __forceinline__ unsigned xb_add(unsigned* p, unsigned v) { return __hip_atomic_fetch_add(p, v, __ATOMIC_RELAXED, __HIP_MEMORY_SCOPE_AGENT); }
; __device__ __forceinline__ void xcd_barrier(const XcdBarrier& b) {
;     ...
;             __builtin_amdgcn_fence(__ATOMIC_ACQUIRE, "agent");
;             xb_add(&bar[XB_XGEN(b.x)], 1u);
;             asm volatile("s_waitcnt vmcnt(0)" ::: "memory");
.LBB0_1219:
	s_or_b64 exec, exec, s[4:5]
	s_mov_b64 s[4:5], exec
	v_mbcnt_lo_u32_b32 v0, s4, 0
	v_mbcnt_hi_u32_b32 v0, s5, v0
	v_cmp_eq_u32_e32 vcc, 0, v0
	s_waitcnt vmcnt(0)
	s_and_saveexec_b64 s[6:7], vcc
	s_cbranch_execz .LBB0_1221
	s_bcnt1_i32_b64 s4, s[4:5]
	v_mov_b32_e32 v0, 0x2000
	v_mov_b32_e32 v1, s4
.LBB0_1221:
	s_or_b64 exec, exec, s[6:7]
	s_waitcnt vmcnt(0)
